# deferred convert extended: also three quarters of layer-2 mlp_w1 moved into the K/V-GEMM idle window (14.7 items per idle wave)
# speedup vs baseline: 1.0040x; 1.0040x over previous
.LBB0_7:
	s_load_dwordx16 s[8:23], s[0:1], 0x40
	s_lshl_b32 s3, s29, 3
	s_mov_b64 s[0:1], s[94:95]
	v_mov_b32_e32 v2, v193
	s_lshl_b32 s86, s96, 3
	s_waitcnt lgkmcnt(0)
	v_writelane_b32 v253, s8, 0
	s_nop 1
	v_writelane_b32 v253, s9, 1
	v_writelane_b32 v253, s10, 2
	v_writelane_b32 v253, s11, 3
	v_writelane_b32 v253, s12, 4
	v_writelane_b32 v253, s13, 5
	v_writelane_b32 v253, s14, 6
	v_writelane_b32 v253, s15, 7
	v_writelane_b32 v253, s16, 8
	v_writelane_b32 v253, s17, 9
	v_writelane_b32 v253, s18, 10
	v_writelane_b32 v253, s19, 11
	v_writelane_b32 v253, s20, 12
	v_writelane_b32 v253, s21, 13
	v_writelane_b32 v253, s22, 14
	v_writelane_b32 v253, s23, 15
	v_writelane_b32 v253, s3, 16
	s_mov_b64 s[8:9], s[92:93]
	v_writelane_b32 v253, s88, 17
	s_mov_b32 s10, s2
	s_nop 0
	v_writelane_b32 v253, s89, 18
	v_writelane_b32 v253, s90, 19
	v_writelane_b32 v253, s91, 20
	v_writelane_b32 v253, s92, 21
	v_writelane_b32 v253, s93, 22
	v_writelane_b32 v253, s94, 23
	v_writelane_b32 v253, s95, 24
	v_writelane_b32 v253, s52, 25
	v_readfirstlane_b32 s8, v2
	s_ashr_i32 s10, s8, 6
	v_writelane_b32 v253, s53, 26
	v_writelane_b32 v253, s54, 27
	v_writelane_b32 v253, s55, 28
	v_writelane_b32 v253, s56, 29
	v_writelane_b32 v253, s57, 30
	v_writelane_b32 v253, s58, 31
	v_writelane_b32 v253, s59, 32
	v_writelane_b32 v253, s60, 33
	v_writelane_b32 v253, s61, 34
	v_writelane_b32 v253, s62, 35
	v_writelane_b32 v253, s63, 36
	v_writelane_b32 v253, s64, 37
	v_writelane_b32 v253, s65, 38
	v_writelane_b32 v253, s66, 39
	s_add_i32 s11, s10, s3
	v_writelane_b32 v253, s67, 40
	s_cmp_gt_i32 s11, 0x161ff
	v_writelane_b32 v253, s29, 41
	s_cbranch_scc1 .LBB0_49
	s_lshl_b32 s8, s10, 14
	s_add_u32 s87, s0, 0x16400000
	s_addc_u32 s88, s1, 0
	s_add_u32 s90, s0, 0x15400000
	s_addc_u32 s91, s1, 0
	s_add_u32 s92, s0, 0x14000000
	s_addc_u32 s21, s1, 0
	s_add_u32 s22, s0, 0x11000000
	s_addc_u32 s23, s1, 0
	s_add_u32 s24, s0, 0x9000000
	v_and_b32_e32 v4, 31, v2
	s_addc_u32 s25, s1, 0
	v_bfe_u32 v1, v2, 5, 1
	v_lshl_or_b32 v3, v4, 2, s8
	s_movk_i32 s9, 0x84
	v_and_b32_e32 v5, 7, v2
	v_bfe_u32 v25, v2, 3, 3
	s_add_u32 s26, s0, 0x1000000
	v_readlane_b32 s60, v253, 0
	v_mov_b32_e32 v11, 0
	v_mad_u32_u24 v24, v1, s9, v3
	v_mul_u32_u24_e32 v2, 0x420, v5
	v_lshlrev_b32_e32 v3, 2, v25
	s_addc_u32 s27, s1, 0
	v_lshlrev_b32_e32 v10, 4, v5
	v_readlane_b32 s64, v253, 4
	v_readlane_b32 s65, v253, 5
	v_or3_b32 v26, s8, v2, v3
	v_lshl_add_u64 v[2:3], s[0:1], 0, v[10:11]
	s_mov_b64 s[0:1], 0x15000000
	s_cmp_lg_u64 s[64:65], 0
	v_lshl_add_u64 v[12:13], v[2:3], 0, s[0:1]
	s_cselect_b64 s[0:1], -1, 0
	s_cmp_lg_u64 s[56:57], 0
	v_lshlrev_b32_e32 v6, 3, v5
	v_lshlrev_b32_e32 v10, 5, v5
	v_readlane_b32 s61, v253, 1
	v_readlane_b32 s62, v253, 2
	v_readlane_b32 s63, v253, 3
	v_readlane_b32 s66, v253, 6
	v_readlane_b32 s67, v253, 7
	v_readlane_b32 s68, v253, 8
	v_readlane_b32 s69, v253, 9
	v_readlane_b32 s70, v253, 10
	v_readlane_b32 s71, v253, 11
	v_readlane_b32 s72, v253, 12
	v_readlane_b32 s73, v253, 13
	v_readlane_b32 s74, v253, 14
	v_readlane_b32 s75, v253, 15
	v_writelane_b32 v253, s0, 42
	s_cselect_b64 s[8:9], -1, 0
	s_add_i32 s28, s11, 0xfffeae00
	s_lshl_b32 s11, s29, 6
	s_lshl_b32 s10, s10, 3
	v_or_b32_e32 v27, 8, v25
	v_or_b32_e32 v28, 16, v25
	v_or_b32_e32 v29, 24, v25
	v_lshl_add_u64 v[14:15], s[64:65], 0, v[10:11]
	v_writelane_b32 v253, s1, 43
	s_add_i32 s29, s11, s10
	s_lshl_b32 s30, s96, 6
	s_movk_i32 s31, 0x4000
	s_mov_b32 s34, 0x8000
	s_mov_b32 s35, 0xc000
	s_mov_b32 s36, 0x10000
	s_mov_b32 s37, 0x14000
	s_mov_b32 s38, 0x18000
	s_mov_b32 s39, 0x1c000
	s_mov_b32 s40, 0x20000
	s_mov_b32 s41, 0x24000
	s_mov_b32 s42, 0x28000
	s_mov_b32 s43, 0x2c000
	s_mov_b32 s44, 0x30000
	s_mov_b32 s45, 0x34000
	s_mov_b32 s46, 0x38000
	s_mov_b32 s47, 0x3c000
	s_mov_b32 s48, 0x40000
	s_mov_b32 s49, 0x44000
	s_mov_b32 s51, 0x48000
	s_mov_b32 s52, 0x4c000
	s_mov_b32 s53, 0x50000
	s_mov_b32 s54, 0x54000
	s_mov_b32 s55, 0x58000
	s_mov_b32 s56, 0x5c000
	s_mov_b32 s57, 0x60000
	s_mov_b32 s58, 0x64000
	s_mov_b32 s59, 0x68000
	s_mov_b32 s60, 0x6c000
	s_mov_b32 s61, 0x70000
	s_mov_b32 s62, 0x74000
	s_mov_b32 s63, 0x78000
	s_mov_b32 s3, 0x7c000
	s_movk_i32 s89, 0x1000
	s_movk_i32 s93, 0x2000
	s_movk_i32 s94, 0x7000
	s_mov_b32 s95, 0x9000
	s_mov_b32 s16, 0xa000
	s_mov_b32 s17, 0xb000
	s_mov_b32 s18, 0xd000
	s_mov_b32 s19, 0xe000
	v_lshlrev_b32_e32 v16, 2, v4
	v_add_u32_e32 v30, 0x400, v24
	v_add_u32_e32 v31, 0x800, v24
	v_add_u32_e32 v32, 0xc00, v24
	v_add_u32_e32 v33, 0x1000, v24
	v_add_u32_e32 v34, 0x1400, v24
	v_add_u32_e32 v35, 0x1800, v24
	v_add_u32_e32 v36, 0x1c00, v24
	v_lshlrev_b32_e32 v18, 1, v6
	v_lshlrev_b32_e32 v20, 2, v6
	s_mov_b32 s0, 0x90000
	s_mov_b32 s1, 0xc0000
	s_mov_b32 s20, 0xf0000
	s_mov_b32 s80, 0x120000
	s_mov_b32 s81, 0x150000
	s_mov_b32 s11, 0
	s_cmp_lg_u32 s96, 0x100
	s_cbranch_scc1 .Lmy_cv_skip
	s_add_i32 s76, s28, 0x15200
	v_lshlrev_b32_e32 v180, 15, v1
	v_or_b32_e32 v180, v180, v16
	v_or_b32_e32 v181, 0, v25
	v_lshlrev_b32_e32 v181, 12, v181
	v_or_b32_e32 v181, v181, v18
	v_or_b32_e32 v182, 8, v25
	v_lshlrev_b32_e32 v182, 12, v182
	v_or_b32_e32 v182, v182, v18
	v_or_b32_e32 v183, 16, v25
	v_lshlrev_b32_e32 v183, 12, v183
	v_or_b32_e32 v183, v183, v18
	v_or_b32_e32 v184, 24, v25
	v_lshlrev_b32_e32 v184, 12, v184
	v_or_b32_e32 v184, v184, v18
	v_readlane_b32 s64, v253, 31
	v_readlane_b32 s65, v253, 32
	v_readlane_b32 s68, v253, 29
	v_readlane_b32 s69, v253, 30
	s_lshr_b32 s77, s76, 8
	s_and_b32 s78, s76, 0xff
	s_lshl_b32 s79, s77, 21
	s_add_u32 s64, s64, s79
	s_addc_u32 s65, s65, 0
	s_lshl_b32 s79, s78, 7
	s_add_u32 s64, s64, s79
	s_addc_u32 s65, s65, 0
	s_lshl_b32 s79, s77, 8
	s_add_u32 s68, s68, s79
	s_addc_u32 s69, s69, 0
	s_lshl_b32 s79, s78, 17
	s_add_u32 s66, s26, s79
	s_addc_u32 s67, s27, 0
	s_lshl_b32 s79, s77, 7
	s_add_u32 s66, s66, s79
	s_addc_u32 s67, s67, 0
	s_mov_b32 s78, 8
	s_mov_b32 s70, 0
	s_mov_b64 s[72:73], s[64:65]
	global_load_dword v100, v180, s[72:73]
	s_add_u32 s72, s72, 0x10000
	s_addc_u32 s73, s73, 0
	global_load_dword v101, v180, s[72:73]
	s_add_u32 s72, s72, 0x10000
	s_addc_u32 s73, s73, 0
	global_load_dword v102, v180, s[72:73]
	s_add_u32 s72, s72, 0x10000
	s_addc_u32 s73, s73, 0
	global_load_dword v103, v180, s[72:73]
	s_add_u32 s72, s72, 0x10000
	s_addc_u32 s73, s73, 0
	global_load_dword v104, v180, s[72:73]
	s_add_u32 s72, s72, 0x10000
	s_addc_u32 s73, s73, 0
	global_load_dword v105, v180, s[72:73]
	s_add_u32 s72, s72, 0x10000
	s_addc_u32 s73, s73, 0
	global_load_dword v106, v180, s[72:73]
	s_add_u32 s72, s72, 0x10000
	s_addc_u32 s73, s73, 0
	global_load_dword v107, v180, s[72:73]
	s_add_u32 s72, s72, 0x10000
	s_addc_u32 s73, s73, 0
	global_load_dword v108, v180, s[72:73]
	s_add_u32 s72, s72, 0x10000
	s_addc_u32 s73, s73, 0
	global_load_dword v109, v180, s[72:73]
	s_add_u32 s72, s72, 0x10000
	s_addc_u32 s73, s73, 0
	global_load_dword v110, v180, s[72:73]
	s_add_u32 s72, s72, 0x10000
	s_addc_u32 s73, s73, 0
	global_load_dword v111, v180, s[72:73]
	s_add_u32 s72, s72, 0x10000
	s_addc_u32 s73, s73, 0
	global_load_dword v112, v180, s[72:73]
	s_add_u32 s72, s72, 0x10000
	s_addc_u32 s73, s73, 0
	global_load_dword v113, v180, s[72:73]
	s_add_u32 s72, s72, 0x10000
	s_addc_u32 s73, s73, 0
	global_load_dword v114, v180, s[72:73]
	s_add_u32 s72, s72, 0x10000
	s_addc_u32 s73, s73, 0
	global_load_dword v115, v180, s[72:73]
	s_add_u32 s72, s72, 0x10000
	s_addc_u32 s73, s73, 0
	global_load_dword v116, v180, s[72:73]
	s_add_u32 s72, s72, 0x10000
	s_addc_u32 s73, s73, 0
	global_load_dword v117, v180, s[72:73]
	s_add_u32 s72, s72, 0x10000
	s_addc_u32 s73, s73, 0
	global_load_dword v118, v180, s[72:73]
	s_add_u32 s72, s72, 0x10000
	s_addc_u32 s73, s73, 0
	global_load_dword v119, v180, s[72:73]
	s_add_u32 s72, s72, 0x10000
	s_addc_u32 s73, s73, 0
	global_load_dword v120, v180, s[72:73]
	s_add_u32 s72, s72, 0x10000
	s_addc_u32 s73, s73, 0
	global_load_dword v121, v180, s[72:73]
	s_add_u32 s72, s72, 0x10000
	s_addc_u32 s73, s73, 0
	global_load_dword v122, v180, s[72:73]
	s_add_u32 s72, s72, 0x10000
	s_addc_u32 s73, s73, 0
	global_load_dword v123, v180, s[72:73]
	s_add_u32 s72, s72, 0x10000
	s_addc_u32 s73, s73, 0
	global_load_dword v124, v180, s[72:73]
	s_add_u32 s72, s72, 0x10000
	s_addc_u32 s73, s73, 0
	global_load_dword v125, v180, s[72:73]
	s_add_u32 s72, s72, 0x10000
	s_addc_u32 s73, s73, 0
	global_load_dword v126, v180, s[72:73]
	s_add_u32 s72, s72, 0x10000
	s_addc_u32 s73, s73, 0
	global_load_dword v127, v180, s[72:73]
	s_add_u32 s72, s72, 0x10000
	s_addc_u32 s73, s73, 0
	global_load_dword v128, v180, s[72:73]
	s_add_u32 s72, s72, 0x10000
	s_addc_u32 s73, s73, 0
	global_load_dword v129, v180, s[72:73]
	s_add_u32 s72, s72, 0x10000
	s_addc_u32 s73, s73, 0
	global_load_dword v130, v180, s[72:73]
	s_add_u32 s72, s72, 0x10000
	s_addc_u32 s73, s73, 0
	global_load_dword v131, v180, s[72:73]
	global_load_dwordx4 v[132:135], v20, s[68:69]
	global_load_dwordx4 v[136:139], v20, s[68:69] offset:16
	s_add_u32 s64, s64, 0x1000000
	s_addc_u32 s65, s65, 0
	s_add_u32 s68, s68, 0x800
	s_addc_u32 s69, s69, 0

.Lmy_cvw1_done:
	s_add_u32 s64, s64, 0x3000000
	s_addc_u32 s65, s65, 0
	s_add_u32 s68, s68, 0x1800
	s_addc_u32 s69, s69, 0
	s_add_u32 s66, s66, 0xc00
	s_addc_u32 s67, s67, 0
	s_mov_b32 s78, 1
	s_mov_b32 s70, 0
	s_mov_b64 s[72:73], s[64:65]
	global_load_dword v100, v180, s[72:73]
	s_add_u32 s72, s72, 0x10000
	s_addc_u32 s73, s73, 0
	global_load_dword v101, v180, s[72:73]
	s_add_u32 s72, s72, 0x10000
	s_addc_u32 s73, s73, 0
	global_load_dword v102, v180, s[72:73]
	s_add_u32 s72, s72, 0x10000
	s_addc_u32 s73, s73, 0
	global_load_dword v103, v180, s[72:73]
	s_add_u32 s72, s72, 0x10000
	s_addc_u32 s73, s73, 0
	global_load_dword v104, v180, s[72:73]
	s_add_u32 s72, s72, 0x10000
	s_addc_u32 s73, s73, 0
	global_load_dword v105, v180, s[72:73]
	s_add_u32 s72, s72, 0x10000
	s_addc_u32 s73, s73, 0
	global_load_dword v106, v180, s[72:73]
	s_add_u32 s72, s72, 0x10000
	s_addc_u32 s73, s73, 0
	global_load_dword v107, v180, s[72:73]
	s_add_u32 s72, s72, 0x10000
	s_addc_u32 s73, s73, 0
	global_load_dword v108, v180, s[72:73]
	s_add_u32 s72, s72, 0x10000
	s_addc_u32 s73, s73, 0
	global_load_dword v109, v180, s[72:73]
	s_add_u32 s72, s72, 0x10000
	s_addc_u32 s73, s73, 0
	global_load_dword v110, v180, s[72:73]
	s_add_u32 s72, s72, 0x10000
	s_addc_u32 s73, s73, 0
	global_load_dword v111, v180, s[72:73]
	s_add_u32 s72, s72, 0x10000
	s_addc_u32 s73, s73, 0
	global_load_dword v112, v180, s[72:73]
	s_add_u32 s72, s72, 0x10000
	s_addc_u32 s73, s73, 0
	global_load_dword v113, v180, s[72:73]
	s_add_u32 s72, s72, 0x10000
	s_addc_u32 s73, s73, 0
	global_load_dword v114, v180, s[72:73]
	s_add_u32 s72, s72, 0x10000
	s_addc_u32 s73, s73, 0
	global_load_dword v115, v180, s[72:73]
	s_add_u32 s72, s72, 0x10000
	s_addc_u32 s73, s73, 0
	global_load_dword v116, v180, s[72:73]
	s_add_u32 s72, s72, 0x10000
	s_addc_u32 s73, s73, 0
	global_load_dword v117, v180, s[72:73]
	s_add_u32 s72, s72, 0x10000
	s_addc_u32 s73, s73, 0
	global_load_dword v118, v180, s[72:73]
	s_add_u32 s72, s72, 0x10000
	s_addc_u32 s73, s73, 0
	global_load_dword v119, v180, s[72:73]
	s_add_u32 s72, s72, 0x10000
	s_addc_u32 s73, s73, 0
	global_load_dword v120, v180, s[72:73]
	s_add_u32 s72, s72, 0x10000
	s_addc_u32 s73, s73, 0
	global_load_dword v121, v180, s[72:73]
	s_add_u32 s72, s72, 0x10000
	s_addc_u32 s73, s73, 0
	global_load_dword v122, v180, s[72:73]
	s_add_u32 s72, s72, 0x10000
	s_addc_u32 s73, s73, 0
	global_load_dword v123, v180, s[72:73]
	s_add_u32 s72, s72, 0x10000
	s_addc_u32 s73, s73, 0
	global_load_dword v124, v180, s[72:73]
	s_add_u32 s72, s72, 0x10000
	s_addc_u32 s73, s73, 0
	global_load_dword v125, v180, s[72:73]
	s_add_u32 s72, s72, 0x10000
	s_addc_u32 s73, s73, 0
	global_load_dword v126, v180, s[72:73]
	s_add_u32 s72, s72, 0x10000
	s_addc_u32 s73, s73, 0
	global_load_dword v127, v180, s[72:73]
	s_add_u32 s72, s72, 0x10000
	s_addc_u32 s73, s73, 0
	global_load_dword v128, v180, s[72:73]
	s_add_u32 s72, s72, 0x10000
	s_addc_u32 s73, s73, 0
	global_load_dword v129, v180, s[72:73]
	s_add_u32 s72, s72, 0x10000
	s_addc_u32 s73, s73, 0
	global_load_dword v130, v180, s[72:73]
	s_add_u32 s72, s72, 0x10000
	s_addc_u32 s73, s73, 0
	global_load_dword v131, v180, s[72:73]
	global_load_dwordx4 v[132:135], v20, s[68:69]
	global_load_dwordx4 v[136:139], v20, s[68:69] offset:16
	s_add_u32 s64, s64, 0x1000000
	s_addc_u32 s65, s65, 0
	s_add_u32 s68, s68, 0x800
	s_addc_u32 s69, s69, 0

.Lmy_deferred:
	s_cmp_lg_u32 s96, 0x100
	s_cbranch_scc1 .LBB0_183
	s_lshr_b32 s24, s8, 6
	s_sub_i32 s25, s26, 64
	s_lshl_b32 s25, s25, 3
	s_add_i32 s24, s25, s24
	v_and_b32_e32 v4, 31, v193
	v_bfe_u32 v1, v193, 5, 1
	v_and_b32_e32 v5, 7, v193
	v_bfe_u32 v25, v193, 3, 3
	s_lshr_b32 s27, s8, 6
	s_lshl_b32 s27, s27, 14
	v_lshl_or_b32 v3, v4, 2, s27
	s_movk_i32 s28, 0x84
	v_mad_u32_u24 v24, v1, s28, v3
	v_mul_u32_u24_e32 v2, 0x420, v5
	v_lshlrev_b32_e32 v3, 2, v25
	v_or3_b32 v26, s27, v2, v3
	v_add_u32_e32 v30, 0x400, v24
	v_add_u32_e32 v31, 0x800, v24
	v_add_u32_e32 v32, 0xc00, v24
	v_add_u32_e32 v33, 0x1000, v24
	v_add_u32_e32 v34, 0x1400, v24
	v_add_u32_e32 v35, 0x1800, v24
	v_add_u32_e32 v36, 0x1c00, v24
	v_lshlrev_b32_e32 v16, 2, v4
	v_lshlrev_b32_e32 v18, 4, v5
	v_lshlrev_b32_e32 v20, 5, v5
	s_cmp_lt_u32 s24, 0x200
	s_cselect_b32 s22, 6, 5
	v_lshlrev_b32_e32 v148, 15, v1
	v_or_b32_e32 v148, v148, v16
	v_or_b32_e32 v149, 0, v25
	v_lshlrev_b32_e32 v149, 12, v149
	v_or_b32_e32 v149, v149, v18
	v_or_b32_e32 v150, 8, v25
	v_lshlrev_b32_e32 v150, 12, v150
	v_or_b32_e32 v150, v150, v18
	v_or_b32_e32 v151, 16, v25
	v_lshlrev_b32_e32 v151, 12, v151
	v_or_b32_e32 v151, v151, v18
	v_or_b32_e32 v152, 24, v25
	v_lshlrev_b32_e32 v152, 12, v152
	v_or_b32_e32 v152, v152, v18
	v_readlane_b32 s12, v253, 31
	v_readlane_b32 s13, v253, 32
	v_readlane_b32 s16, v253, 29
	v_readlane_b32 s17, v253, 30
	s_lshr_b32 s29, s24, 8
	s_and_b32 s30, s24, 0xff
	s_add_u32 s12, s12, 0x8000000
	s_addc_u32 s13, s13, 0
	s_lshl_b32 s31, s29, 21
	s_add_u32 s12, s12, s31
	s_addc_u32 s13, s13, 0
	s_lshl_b32 s31, s30, 7
	s_add_u32 s12, s12, s31
	s_addc_u32 s13, s13, 0
	s_add_u32 s16, s16, 0x4000
	s_addc_u32 s17, s17, 0
	s_lshl_b32 s31, s29, 8
	s_add_u32 s16, s16, s31
	s_addc_u32 s17, s17, 0
	s_add_u32 s14, s94, 0x5000000
	s_addc_u32 s15, s95, 0
	s_lshl_b32 s31, s30, 17
	s_add_u32 s14, s14, s31
	s_addc_u32 s15, s15, 0
	s_lshl_b32 s31, s29, 7
	s_add_u32 s14, s14, s31
	s_addc_u32 s15, s15, 0
	s_mov_b32 s1, s22
	s_mov_b32 s22, 4
	s_mov_b32 s20, 0
	s_mov_b64 s[18:19], s[12:13]
	global_load_dword v100, v148, s[18:19]
	s_add_u32 s18, s18, 0x10000
	s_addc_u32 s19, s19, 0
	global_load_dword v101, v148, s[18:19]
	s_add_u32 s18, s18, 0x10000
	s_addc_u32 s19, s19, 0
	global_load_dword v102, v148, s[18:19]
	s_add_u32 s18, s18, 0x10000
	s_addc_u32 s19, s19, 0
	global_load_dword v103, v148, s[18:19]
	s_add_u32 s18, s18, 0x10000
	s_addc_u32 s19, s19, 0
	global_load_dword v104, v148, s[18:19]
	s_add_u32 s18, s18, 0x10000
	s_addc_u32 s19, s19, 0
	global_load_dword v105, v148, s[18:19]
	s_add_u32 s18, s18, 0x10000
	s_addc_u32 s19, s19, 0
	global_load_dword v106, v148, s[18:19]
	s_add_u32 s18, s18, 0x10000
	s_addc_u32 s19, s19, 0
	global_load_dword v107, v148, s[18:19]
	s_add_u32 s18, s18, 0x10000
	s_addc_u32 s19, s19, 0
	global_load_dword v108, v148, s[18:19]
	s_add_u32 s18, s18, 0x10000
	s_addc_u32 s19, s19, 0
	global_load_dword v109, v148, s[18:19]
	s_add_u32 s18, s18, 0x10000
	s_addc_u32 s19, s19, 0
	global_load_dword v110, v148, s[18:19]
	s_add_u32 s18, s18, 0x10000
	s_addc_u32 s19, s19, 0
	global_load_dword v111, v148, s[18:19]
	s_add_u32 s18, s18, 0x10000
	s_addc_u32 s19, s19, 0
	global_load_dword v112, v148, s[18:19]
	s_add_u32 s18, s18, 0x10000
	s_addc_u32 s19, s19, 0
	global_load_dword v113, v148, s[18:19]
	s_add_u32 s18, s18, 0x10000
	s_addc_u32 s19, s19, 0
	global_load_dword v114, v148, s[18:19]
	s_add_u32 s18, s18, 0x10000
	s_addc_u32 s19, s19, 0
	global_load_dword v115, v148, s[18:19]
	s_add_u32 s18, s18, 0x10000
	s_addc_u32 s19, s19, 0
	global_load_dword v116, v148, s[18:19]
	s_add_u32 s18, s18, 0x10000
	s_addc_u32 s19, s19, 0
	global_load_dword v117, v148, s[18:19]
	s_add_u32 s18, s18, 0x10000
	s_addc_u32 s19, s19, 0
	global_load_dword v118, v148, s[18:19]
	s_add_u32 s18, s18, 0x10000
	s_addc_u32 s19, s19, 0
	global_load_dword v119, v148, s[18:19]
	s_add_u32 s18, s18, 0x10000
	s_addc_u32 s19, s19, 0
	global_load_dword v120, v148, s[18:19]
	s_add_u32 s18, s18, 0x10000
	s_addc_u32 s19, s19, 0
	global_load_dword v121, v148, s[18:19]
	s_add_u32 s18, s18, 0x10000
	s_addc_u32 s19, s19, 0
	global_load_dword v122, v148, s[18:19]
	s_add_u32 s18, s18, 0x10000
	s_addc_u32 s19, s19, 0
	global_load_dword v123, v148, s[18:19]
	s_add_u32 s18, s18, 0x10000
	s_addc_u32 s19, s19, 0
	global_load_dword v124, v148, s[18:19]
	s_add_u32 s18, s18, 0x10000
	s_addc_u32 s19, s19, 0
	global_load_dword v125, v148, s[18:19]
	s_add_u32 s18, s18, 0x10000
	s_addc_u32 s19, s19, 0
	global_load_dword v126, v148, s[18:19]
	s_add_u32 s18, s18, 0x10000
	s_addc_u32 s19, s19, 0
	global_load_dword v127, v148, s[18:19]
	s_add_u32 s18, s18, 0x10000
	s_addc_u32 s19, s19, 0
	global_load_dword v128, v148, s[18:19]
	s_add_u32 s18, s18, 0x10000
	s_addc_u32 s19, s19, 0
	global_load_dword v129, v148, s[18:19]
	s_add_u32 s18, s18, 0x10000
	s_addc_u32 s19, s19, 0
	global_load_dword v130, v148, s[18:19]
	s_add_u32 s18, s18, 0x10000
	s_addc_u32 s19, s19, 0
	global_load_dword v131, v148, s[18:19]
	global_load_dwordx4 v[132:135], v20, s[16:17]
	global_load_dwordx4 v[136:139], v20, s[16:17] offset:16
	s_add_u32 s12, s12, 0xc00000
	s_addc_u32 s13, s13, 0
	s_add_u32 s16, s16, 0x600
	s_addc_u32 s17, s17, 0

.Lmy_dfw1l2_done:
	s_mov_b32 s22, s1
	v_lshlrev_b32_e32 v148, 15, v1
	v_or_b32_e32 v148, v148, v16
	v_or_b32_e32 v149, 0, v25
	v_lshlrev_b32_e32 v149, 12, v149
	v_or_b32_e32 v149, v149, v18
	v_or_b32_e32 v150, 8, v25
	v_lshlrev_b32_e32 v150, 12, v150
	v_or_b32_e32 v150, v150, v18
	v_or_b32_e32 v151, 16, v25
	v_lshlrev_b32_e32 v151, 12, v151
	v_or_b32_e32 v151, v151, v18
	v_or_b32_e32 v152, 24, v25
	v_lshlrev_b32_e32 v152, 12, v152
	v_or_b32_e32 v152, v152, v18
	v_readlane_b32 s12, v253, 31
	v_readlane_b32 s13, v253, 32
	v_readlane_b32 s16, v253, 29
	v_readlane_b32 s17, v253, 30
	s_lshr_b32 s29, s24, 8
	s_and_b32 s30, s24, 0xff
	s_add_u32 s12, s12, 0xc000000
	s_addc_u32 s13, s13, 0
	s_lshl_b32 s31, s29, 21
	s_add_u32 s12, s12, s31
	s_addc_u32 s13, s13, 0
	s_lshl_b32 s31, s30, 7
	s_add_u32 s12, s12, s31
	s_addc_u32 s13, s13, 0
	s_add_u32 s16, s16, 0x6000
	s_addc_u32 s17, s17, 0
	s_lshl_b32 s31, s29, 8
	s_add_u32 s16, s16, s31
	s_addc_u32 s17, s17, 0
	s_add_u32 s14, s94, 0x7000000
	s_addc_u32 s15, s95, 0
	s_lshl_b32 s31, s30, 17
	s_add_u32 s14, s14, s31
	s_addc_u32 s15, s15, 0
	s_lshl_b32 s31, s29, 7
	s_add_u32 s14, s14, s31
	s_addc_u32 s15, s15, 0
	s_mov_b32 s20, 0
	s_mov_b64 s[18:19], s[12:13]
	global_load_dword v100, v148, s[18:19]
	s_add_u32 s18, s18, 0x10000
	s_addc_u32 s19, s19, 0
	global_load_dword v101, v148, s[18:19]
	s_add_u32 s18, s18, 0x10000
	s_addc_u32 s19, s19, 0
	global_load_dword v102, v148, s[18:19]
	s_add_u32 s18, s18, 0x10000
	s_addc_u32 s19, s19, 0
	global_load_dword v103, v148, s[18:19]
	s_add_u32 s18, s18, 0x10000
	s_addc_u32 s19, s19, 0
	global_load_dword v104, v148, s[18:19]
	s_add_u32 s18, s18, 0x10000
	s_addc_u32 s19, s19, 0
	global_load_dword v105, v148, s[18:19]
	s_add_u32 s18, s18, 0x10000
	s_addc_u32 s19, s19, 0
	global_load_dword v106, v148, s[18:19]
	s_add_u32 s18, s18, 0x10000
	s_addc_u32 s19, s19, 0
	global_load_dword v107, v148, s[18:19]
	s_add_u32 s18, s18, 0x10000
	s_addc_u32 s19, s19, 0
	global_load_dword v108, v148, s[18:19]
	s_add_u32 s18, s18, 0x10000
	s_addc_u32 s19, s19, 0
	global_load_dword v109, v148, s[18:19]
	s_add_u32 s18, s18, 0x10000
	s_addc_u32 s19, s19, 0
	global_load_dword v110, v148, s[18:19]
	s_add_u32 s18, s18, 0x10000
	s_addc_u32 s19, s19, 0
	global_load_dword v111, v148, s[18:19]
	s_add_u32 s18, s18, 0x10000
	s_addc_u32 s19, s19, 0
	global_load_dword v112, v148, s[18:19]
	s_add_u32 s18, s18, 0x10000
	s_addc_u32 s19, s19, 0
	global_load_dword v113, v148, s[18:19]
	s_add_u32 s18, s18, 0x10000
	s_addc_u32 s19, s19, 0
	global_load_dword v114, v148, s[18:19]
	s_add_u32 s18, s18, 0x10000
	s_addc_u32 s19, s19, 0
	global_load_dword v115, v148, s[18:19]
	s_add_u32 s18, s18, 0x10000
	s_addc_u32 s19, s19, 0
	global_load_dword v116, v148, s[18:19]
	s_add_u32 s18, s18, 0x10000
	s_addc_u32 s19, s19, 0
	global_load_dword v117, v148, s[18:19]
	s_add_u32 s18, s18, 0x10000
	s_addc_u32 s19, s19, 0
	global_load_dword v118, v148, s[18:19]
	s_add_u32 s18, s18, 0x10000
	s_addc_u32 s19, s19, 0
	global_load_dword v119, v148, s[18:19]
	s_add_u32 s18, s18, 0x10000
	s_addc_u32 s19, s19, 0
	global_load_dword v120, v148, s[18:19]
	s_add_u32 s18, s18, 0x10000
	s_addc_u32 s19, s19, 0
	global_load_dword v121, v148, s[18:19]
	s_add_u32 s18, s18, 0x10000
	s_addc_u32 s19, s19, 0
	global_load_dword v122, v148, s[18:19]
	s_add_u32 s18, s18, 0x10000
	s_addc_u32 s19, s19, 0
	global_load_dword v123, v148, s[18:19]
	s_add_u32 s18, s18, 0x10000
	s_addc_u32 s19, s19, 0
	global_load_dword v124, v148, s[18:19]
	s_add_u32 s18, s18, 0x10000
	s_addc_u32 s19, s19, 0
	global_load_dword v125, v148, s[18:19]
	s_add_u32 s18, s18, 0x10000
	s_addc_u32 s19, s19, 0
	global_load_dword v126, v148, s[18:19]
	s_add_u32 s18, s18, 0x10000
	s_addc_u32 s19, s19, 0
	global_load_dword v127, v148, s[18:19]
	s_add_u32 s18, s18, 0x10000
	s_addc_u32 s19, s19, 0
	global_load_dword v128, v148, s[18:19]
	s_add_u32 s18, s18, 0x10000
	s_addc_u32 s19, s19, 0
	global_load_dword v129, v148, s[18:19]
	s_add_u32 s18, s18, 0x10000
	s_addc_u32 s19, s19, 0
	global_load_dword v130, v148, s[18:19]
	s_add_u32 s18, s18, 0x10000
	s_addc_u32 s19, s19, 0
	global_load_dword v131, v148, s[18:19]
	global_load_dwordx4 v[132:135], v20, s[16:17]
	global_load_dwordx4 v[136:139], v20, s[16:17] offset:16
	s_add_u32 s12, s12, 0xc00000
	s_addc_u32 s13, s13, 0
	s_add_u32 s16, s16, 0x600
	s_addc_u32 s17, s17, 0
